# P0 cache-latent bf16 conversion: 8 serialized load-convert-store steps per thread replaced by one 16-load burst (fast path for the 256-workgroup grid, generic loop kept as fallback)
# baseline (speedup 1.0000x reference)
; DI unsigned pk2(float lo, float hi) { f32x2 v = {lo, hi}; bf16x2_t b = __builtin_convertvector(v, bf16x2_t); return __builtin_bit_cast(unsigned, b); }
; #define PIN(i) gptr(P.in[i])
; __global__ void __launch_bounds__(512, 2) mega(Params P) {
;     ...
;             bf16_t* CLB = WSP(bf16_t, WS_CLB);
;             const size_t n8 = (size_t)2 * 16384 * 256 / 8;
;             const float* src = PIN(I_CLAT);
; #pragma unroll 4
;             for (size_t i = (size_t)bid * 512 + tid; i < n8; i += (size_t)G * 512) {
;                 const f32x4 a = *(const f32x4*)(src + i * 8), b = *(const f32x4*)(src + i * 8 + 4);
;                 u32x4 w; w.x = pk2(a[0], a[1]); w.y = pk2(a[2], a[3]); w.z = pk2(b[0], b[1]); w.w = pk2(b[2], b[3]);
;                 *(u32x4*)(CLB + i * 8) = w;
;             }
.LBB0_168:
	s_cmp_lg_u32 s78, 0x100
	s_cbranch_scc1 .Lclb_orig
	v_lshl_add_u32 v141, s6, 9, v12
	v_lshlrev_b32_e32 v142, 5, v141
	v_lshlrev_b32_e32 v143, 4, v141
	s_add_u32 s80, s8, 0x3720000
	s_addc_u32 s81, s9, 0
	global_load_dwordx4 v[150:153], v142, s[64:65]
	global_load_dwordx4 v[154:157], v142, s[64:65] offset:16
	v_add_u32_e32 v142, 0x400000, v142
	global_load_dwordx4 v[158:161], v142, s[64:65]
	global_load_dwordx4 v[162:165], v142, s[64:65] offset:16
	v_add_u32_e32 v142, 0x400000, v142
	global_load_dwordx4 v[166:169], v142, s[64:65]
	global_load_dwordx4 v[170:173], v142, s[64:65] offset:16
	v_add_u32_e32 v142, 0x400000, v142
	global_load_dwordx4 v[174:177], v142, s[64:65]
	global_load_dwordx4 v[178:181], v142, s[64:65] offset:16
	v_add_u32_e32 v142, 0x400000, v142
	global_load_dwordx4 v[182:185], v142, s[64:65]
	global_load_dwordx4 v[186:189], v142, s[64:65] offset:16
	v_add_u32_e32 v142, 0x400000, v142
	global_load_dwordx4 v[190:193], v142, s[64:65]
	global_load_dwordx4 v[194:197], v142, s[64:65] offset:16
	v_add_u32_e32 v142, 0x400000, v142
	global_load_dwordx4 v[198:201], v142, s[64:65]
	global_load_dwordx4 v[202:205], v142, s[64:65] offset:16
	v_add_u32_e32 v142, 0x400000, v142
	global_load_dwordx4 v[206:209], v142, s[64:65]
	global_load_dwordx4 v[210:213], v142, s[64:65] offset:16
	s_waitcnt vmcnt(14)
	v_cvt_pk_bf16_f32 v150, v150, v151
	v_cvt_pk_bf16_f32 v151, v152, v153
	v_cvt_pk_bf16_f32 v152, v154, v155
	v_cvt_pk_bf16_f32 v153, v156, v157
	s_waitcnt vmcnt(12)
	v_cvt_pk_bf16_f32 v158, v158, v159
	v_cvt_pk_bf16_f32 v159, v160, v161
	v_cvt_pk_bf16_f32 v160, v162, v163
	v_cvt_pk_bf16_f32 v161, v164, v165
	s_waitcnt vmcnt(10)
	v_cvt_pk_bf16_f32 v166, v166, v167
	v_cvt_pk_bf16_f32 v167, v168, v169
	v_cvt_pk_bf16_f32 v168, v170, v171
	v_cvt_pk_bf16_f32 v169, v172, v173
	s_waitcnt vmcnt(8)
	v_cvt_pk_bf16_f32 v174, v174, v175
	v_cvt_pk_bf16_f32 v175, v176, v177
	v_cvt_pk_bf16_f32 v176, v178, v179
	v_cvt_pk_bf16_f32 v177, v180, v181
	s_waitcnt vmcnt(6)
	v_cvt_pk_bf16_f32 v182, v182, v183
	v_cvt_pk_bf16_f32 v183, v184, v185
	v_cvt_pk_bf16_f32 v184, v186, v187
	v_cvt_pk_bf16_f32 v185, v188, v189
	s_waitcnt vmcnt(4)
	v_cvt_pk_bf16_f32 v190, v190, v191
	v_cvt_pk_bf16_f32 v191, v192, v193
	v_cvt_pk_bf16_f32 v192, v194, v195
	v_cvt_pk_bf16_f32 v193, v196, v197
	s_waitcnt vmcnt(2)
	v_cvt_pk_bf16_f32 v198, v198, v199
	v_cvt_pk_bf16_f32 v199, v200, v201
	v_cvt_pk_bf16_f32 v200, v202, v203
	v_cvt_pk_bf16_f32 v201, v204, v205
	s_waitcnt vmcnt(0)
	v_cvt_pk_bf16_f32 v206, v206, v207
	v_cvt_pk_bf16_f32 v207, v208, v209
	v_cvt_pk_bf16_f32 v208, v210, v211
	v_cvt_pk_bf16_f32 v209, v212, v213
	global_store_dwordx4 v143, v[150:153], s[80:81]
	v_add_u32_e32 v143, 0x200000, v143
	global_store_dwordx4 v143, v[158:161], s[80:81]
	v_add_u32_e32 v143, 0x200000, v143
	global_store_dwordx4 v143, v[166:169], s[80:81]
	v_add_u32_e32 v143, 0x200000, v143
	global_store_dwordx4 v143, v[174:177], s[80:81]
	v_add_u32_e32 v143, 0x200000, v143
	global_store_dwordx4 v143, v[182:185], s[80:81]
	v_add_u32_e32 v143, 0x200000, v143
	global_store_dwordx4 v143, v[190:193], s[80:81]
	v_add_u32_e32 v143, 0x200000, v143
	global_store_dwordx4 v143, v[198:201], s[80:81]
	v_add_u32_e32 v143, 0x200000, v143
	global_store_dwordx4 v143, v[206:209], s[80:81]
	s_ashr_i32 s77, s78, 31
	s_mov_b32 s76, s78
	v_readlane_b32 s15, v253, 32
	s_branch .LBB0_177
